# P5 gain loads issued before the row-statistics exchange
# baseline (speedup 1.0000x reference)
.LBB0_654:
	s_lshl_b32 s0, s8, 8
	s_or_b32 s0, s0, s34
	v_or_b32_e32 v194, s0, v220
	v_mov_b32_e32 v196, s78
	v_mov_b32_e32 v197, s79
	v_ashrrev_i32_e32 v195, 31, v194
	v_lshl_add_u64 v[194:195], v[194:195], 2, v[196:197]
	global_load_dwordx4 v[178:181], v[194:195], off
	global_load_dwordx4 v[182:185], v[194:195], off offset:64
	global_load_dwordx4 v[186:189], v[194:195], off offset:512
	global_load_dwordx4 v[190:193], v[194:195], off offset:576
	v_xor_b32_e32 v130, 16, v244
	v_cmp_lt_i32_e32 vcc, v130, v246
	v_cndmask_b32_e32 v130, v244, v130, vcc
	v_lshlrev_b32_e32 v130, 2, v130
	v_mul_f32_e32 v140, v127, v127
	v_mul_f32_e32 v150, v129, v129
	v_fmac_f32_e32 v140, v126, v126
	v_fmac_f32_e32 v150, v128, v128
	v_add_f32_e32 v140, v140, v150
	v_mul_f32_e32 v150, v123, v123
	v_mul_f32_e32 v160, v125, v125
	v_fmac_f32_e32 v150, v122, v122
	v_fmac_f32_e32 v160, v124, v124
	v_add_f32_e32 v150, v150, v160
	v_add_f32_e32 v140, v150, v140
	v_mul_f32_e32 v150, v115, v115
	v_mul_f32_e32 v160, v117, v117
	v_fmac_f32_e32 v150, v114, v114
	v_fmac_f32_e32 v160, v116, v116
	v_add_f32_e32 v150, v150, v160
	v_add_f32_e32 v140, v150, v140
	v_mul_f32_e32 v150, v111, v111
	v_mul_f32_e32 v160, v113, v113
	v_fmac_f32_e32 v150, v110, v110
	v_fmac_f32_e32 v160, v112, v112
	v_add_f32_e32 v150, v150, v160
	v_add_f32_e32 v140, v150, v140
	v_mul_f32_e32 v141, v119, v119
	v_mul_f32_e32 v151, v121, v121
	v_fmac_f32_e32 v141, v118, v118
	v_fmac_f32_e32 v151, v120, v120
	v_add_f32_e32 v141, v141, v151
	v_mul_f32_e32 v151, v107, v107
	v_mul_f32_e32 v161, v109, v109
	v_fmac_f32_e32 v151, v106, v106
	v_fmac_f32_e32 v161, v108, v108
	v_add_f32_e32 v151, v151, v161
	v_add_f32_e32 v141, v151, v141
	v_mul_f32_e32 v151, v103, v103
	v_mul_f32_e32 v161, v105, v105
	v_fmac_f32_e32 v151, v102, v102
	v_fmac_f32_e32 v161, v104, v104
	v_add_f32_e32 v151, v151, v161
	v_add_f32_e32 v141, v151, v141
	v_mul_f32_e32 v151, v91, v91
	v_mul_f32_e32 v161, v93, v93
	v_fmac_f32_e32 v151, v90, v90
	v_fmac_f32_e32 v161, v92, v92
	v_add_f32_e32 v151, v151, v161
	v_add_f32_e32 v141, v151, v141
	v_mul_f32_e32 v142, v95, v95
	v_mul_f32_e32 v152, v97, v97
	v_fmac_f32_e32 v142, v94, v94
	v_fmac_f32_e32 v152, v96, v96
	v_add_f32_e32 v142, v142, v152
	v_mul_f32_e32 v152, v83, v83
	v_mul_f32_e32 v162, v85, v85
	v_fmac_f32_e32 v152, v82, v82
	v_fmac_f32_e32 v162, v84, v84
	v_add_f32_e32 v152, v152, v162
	v_add_f32_e32 v142, v152, v142
	v_mul_f32_e32 v152, v71, v71
	v_mul_f32_e32 v162, v73, v73
	v_fmac_f32_e32 v152, v70, v70
	v_fmac_f32_e32 v162, v72, v72
	v_add_f32_e32 v152, v152, v162
	v_add_f32_e32 v142, v152, v142
	v_mul_f32_e32 v152, v59, v59
	v_mul_f32_e32 v162, v61, v61
	v_fmac_f32_e32 v152, v58, v58
	v_fmac_f32_e32 v162, v60, v60
	v_add_f32_e32 v152, v152, v162
	v_add_f32_e32 v142, v152, v142
	v_mul_f32_e32 v143, v63, v63
	v_mul_f32_e32 v153, v65, v65
	v_fmac_f32_e32 v143, v62, v62
	v_fmac_f32_e32 v153, v64, v64
	v_add_f32_e32 v143, v143, v153
	v_mul_f32_e32 v153, v67, v67
	v_mul_f32_e32 v163, v69, v69
	v_fmac_f32_e32 v153, v66, v66
	v_fmac_f32_e32 v163, v68, v68
	v_add_f32_e32 v153, v153, v163
	v_add_f32_e32 v143, v153, v143
	v_mul_f32_e32 v153, v99, v99
	v_mul_f32_e32 v163, v101, v101
	v_fmac_f32_e32 v153, v98, v98
	v_fmac_f32_e32 v163, v100, v100
	v_add_f32_e32 v153, v153, v163
	v_add_f32_e32 v143, v153, v143
	v_mul_f32_e32 v153, v87, v87
	v_mul_f32_e32 v163, v89, v89
	v_fmac_f32_e32 v153, v86, v86
	v_fmac_f32_e32 v163, v88, v88
	v_add_f32_e32 v153, v153, v163
	v_add_f32_e32 v143, v153, v143
	v_mul_f32_e32 v144, v79, v79
	v_mul_f32_e32 v154, v81, v81
	v_fmac_f32_e32 v144, v78, v78
	v_fmac_f32_e32 v154, v80, v80
	v_add_f32_e32 v144, v144, v154
	v_mul_f32_e32 v154, v75, v75
	v_mul_f32_e32 v164, v77, v77
	v_fmac_f32_e32 v154, v74, v74
	v_fmac_f32_e32 v164, v76, v76
	v_add_f32_e32 v154, v154, v164
	v_add_f32_e32 v144, v154, v144
	v_mul_f32_e32 v154, v55, v55
	v_mul_f32_e32 v164, v57, v57
	v_fmac_f32_e32 v154, v54, v54
	v_fmac_f32_e32 v164, v56, v56
	v_add_f32_e32 v154, v154, v164
	v_add_f32_e32 v144, v154, v144
	v_mul_f32_e32 v154, v47, v47
	v_mul_f32_e32 v164, v49, v49
	v_fmac_f32_e32 v154, v46, v46
	v_fmac_f32_e32 v164, v48, v48
	v_add_f32_e32 v154, v154, v164
	v_add_f32_e32 v144, v154, v144
	v_mul_f32_e32 v145, v51, v51
	v_mul_f32_e32 v155, v53, v53
	v_fmac_f32_e32 v145, v50, v50
	v_fmac_f32_e32 v155, v52, v52
	v_add_f32_e32 v145, v145, v155
	v_mul_f32_e32 v155, v43, v43
	v_mul_f32_e32 v165, v45, v45
	v_fmac_f32_e32 v155, v42, v42
	v_fmac_f32_e32 v165, v44, v44
	v_add_f32_e32 v155, v155, v165
	v_add_f32_e32 v145, v155, v145
	v_mul_f32_e32 v155, v39, v39
	v_mul_f32_e32 v165, v41, v41
	v_fmac_f32_e32 v155, v38, v38
	v_fmac_f32_e32 v165, v40, v40
	v_add_f32_e32 v155, v155, v165
	v_add_f32_e32 v145, v155, v145
	v_mul_f32_e32 v155, v31, v31
	v_mul_f32_e32 v165, v33, v33
	v_fmac_f32_e32 v155, v30, v30
	v_fmac_f32_e32 v165, v32, v32
	v_add_f32_e32 v155, v155, v165
	v_add_f32_e32 v145, v155, v145
	v_mul_f32_e32 v146, v35, v35
	v_mul_f32_e32 v156, v37, v37
	v_fmac_f32_e32 v146, v34, v34
	v_fmac_f32_e32 v156, v36, v36
	v_add_f32_e32 v146, v146, v156
	v_mul_f32_e32 v156, v27, v27
	v_mul_f32_e32 v166, v29, v29
	v_fmac_f32_e32 v156, v26, v26
	v_fmac_f32_e32 v166, v28, v28
	v_add_f32_e32 v156, v156, v166
	v_add_f32_e32 v146, v156, v146
	v_mul_f32_e32 v156, v23, v23
	v_mul_f32_e32 v166, v25, v25
	v_fmac_f32_e32 v156, v22, v22
	v_fmac_f32_e32 v166, v24, v24
	v_add_f32_e32 v156, v156, v166
	v_add_f32_e32 v146, v156, v146
	v_mul_f32_e32 v156, v15, v15
	v_mul_f32_e32 v166, v17, v17
	v_fmac_f32_e32 v156, v14, v14
	v_fmac_f32_e32 v166, v16, v16
	v_add_f32_e32 v156, v156, v166
	v_add_f32_e32 v146, v156, v146
	v_mul_f32_e32 v147, v19, v19
	v_mul_f32_e32 v157, v21, v21
	v_fmac_f32_e32 v147, v18, v18
	v_fmac_f32_e32 v157, v20, v20
	v_add_f32_e32 v147, v147, v157
	v_mul_f32_e32 v157, v11, v11
	v_mul_f32_e32 v167, v13, v13
	v_fmac_f32_e32 v157, v10, v10
	v_fmac_f32_e32 v167, v12, v12
	v_add_f32_e32 v157, v157, v167
	v_add_f32_e32 v147, v157, v147
	v_mul_f32_e32 v157, v7, v7
	v_mul_f32_e32 v167, v9, v9
	v_fmac_f32_e32 v157, v6, v6
	v_fmac_f32_e32 v167, v8, v8
	v_add_f32_e32 v157, v157, v167
	v_add_f32_e32 v147, v157, v147
	v_mul_f32_e32 v157, v3, v3
	v_mul_f32_e32 v167, v5, v5
	v_fmac_f32_e32 v157, v2, v2
	v_fmac_f32_e32 v167, v4, v4
	v_add_f32_e32 v157, v157, v167
	v_add_f32_e32 v147, v157, v147
	s_lshl_b32 s0, s37, 2
	v_cmp_gt_u32_e32 vcc, 16, v1
	s_add_i32 s2, s0, 0
	s_barrier
	ds_bpermute_b32 v170, v130, v140
	ds_bpermute_b32 v171, v130, v141
	ds_bpermute_b32 v172, v130, v142
	ds_bpermute_b32 v173, v130, v143
	ds_bpermute_b32 v174, v130, v144
	ds_bpermute_b32 v175, v130, v145
	ds_bpermute_b32 v176, v130, v146
	ds_bpermute_b32 v177, v130, v147
	s_waitcnt lgkmcnt(0)
	v_add_f32_e32 v140, v140, v170
	v_add_f32_e32 v141, v141, v171
	v_add_f32_e32 v142, v142, v172
	v_add_f32_e32 v143, v143, v173
	v_add_f32_e32 v144, v144, v174
	v_add_f32_e32 v145, v145, v175
	v_add_f32_e32 v146, v146, v176
	v_add_f32_e32 v147, v147, v177
	ds_bpermute_b32 v170, v245, v140
	ds_bpermute_b32 v171, v245, v141
	ds_bpermute_b32 v172, v245, v142
	ds_bpermute_b32 v173, v245, v143
	ds_bpermute_b32 v174, v245, v144
	ds_bpermute_b32 v175, v245, v145
	ds_bpermute_b32 v176, v245, v146
	ds_bpermute_b32 v177, v245, v147
	s_and_saveexec_b64 s[0:1], vcc
	s_cbranch_execz .LBB0_670
	s_lshl_b32 s3, s9, 10
	s_add_i32 s3, s2, s3
	v_add_u32_e32 v133, s3, v221
	s_waitcnt lgkmcnt(0)
	v_add_f32_e32 v140, v140, v170
	v_add_f32_e32 v141, v141, v171
	v_add_f32_e32 v142, v142, v172
	v_add_f32_e32 v143, v143, v173
	v_add_f32_e32 v144, v144, v174
	v_add_f32_e32 v145, v145, v175
	v_add_f32_e32 v146, v146, v176
	v_add_f32_e32 v147, v147, v177
	ds_write_b32 v133, v140
	ds_write_b32 v133, v141 offset:256
	ds_write_b32 v133, v142 offset:512
	ds_write_b32 v133, v143 offset:768
	ds_write_b32 v133, v144 offset:2048
	ds_write_b32 v133, v145 offset:2304
	ds_write_b32 v133, v146 offset:2560
	ds_write_b32 v133, v147 offset:2816

.LBB0_694:
	s_or_b64 exec, exec, s[2:3]
	s_lshl_b32 s0, s8, 8
	s_or_b32 s0, s0, s34
	v_or_b32_e32 v132, s0, v220
	v_mov_b32_e32 v130, s78
	s_waitcnt lgkmcnt(0)
	v_mov_b32_e32 v131, s79
	v_ashrrev_i32_e32 v133, 31, v132
	s_waitcnt lgkmcnt(0)
	s_barrier
	v_lshl_add_u64 v[130:131], v[132:133], 2, v[130:131]
	s_waitcnt vmcnt(0)
	v_mov_b64_e32 v[142:143], v[178:179]
	v_mov_b64_e32 v[144:145], v[180:181]
	v_mov_b64_e32 v[138:139], v[182:183]
	v_mov_b64_e32 v[140:141], v[184:185]
	v_mov_b64_e32 v[134:135], v[186:187]
	v_mov_b64_e32 v[136:137], v[188:189]
	v_mov_b64_e32 v[130:131], v[190:191]
	v_mov_b64_e32 v[132:133], v[192:193]
	s_lshl_b32 s1, s33, 2
	s_add_i32 s1, s1, 0
	v_lshl_add_u32 v151, v231, 2, s1
	v_add_u32_e32 v151, 0x2000, v151
	ds_read2_b32 v[156:157], v151 offset1:16
	v_and_b32_e32 v0, 60, v0
	v_or_b32_e32 v1, s33, v206
	v_lshl_or_b32 v148, v207, 6, v0
	v_add_u32_e32 v0, s4, v1
	s_waitcnt lgkmcnt(0)
	v_pk_mul_f32 v[128:129], v[156:157], v[128:129] op_sel_hi:[0,1]
	v_pk_mul_f32 v[126:127], v[156:157], v[126:127] op_sel_hi:[0,1]
	v_pk_mul_f32 v[124:125], v[156:157], v[124:125] op_sel_hi:[0,1]
	v_pk_mul_f32 v[122:123], v[156:157], v[122:123] op_sel_hi:[0,1]
	v_pk_mul_f32 v[116:117], v[156:157], v[116:117] op_sel_hi:[0,1]
	v_pk_mul_f32 v[114:115], v[156:157], v[114:115] op_sel_hi:[0,1]
	v_pk_mul_f32 v[112:113], v[156:157], v[112:113] op_sel_hi:[0,1]
	v_pk_mul_f32 v[110:111], v[156:157], v[110:111] op_sel_hi:[0,1]
	v_mov_b32_e32 v156, v157
	v_mov_b32_e32 v149, 0x7fc00000
	v_ashrrev_i32_e32 v1, 31, v0
	v_pk_mul_f32 v[120:121], v[156:157], v[120:121] op_sel_hi:[0,1]
	v_pk_mul_f32 v[118:119], v[156:157], v[118:119] op_sel_hi:[0,1]
	v_cmp_eq_u32_e32 vcc, 0, v150
	v_lshlrev_b64 v[154:155], 12, v[0:1]
	v_lshl_or_b32 v146, v207, 2, s0
	v_ashrrev_i32_e32 v147, 31, v146
	v_lshl_add_u64 v[154:155], s[80:81], 0, v[154:155]
	v_lshlrev_b64 v[146:147], 2, v[146:147]
	v_lshl_add_u64 v[154:155], v[154:155], 0, v[146:147]
	v_or_b32_e32 v152, 16, v0
	v_ashrrev_i32_e32 v153, 31, v152
	s_waitcnt vmcnt(0)
	v_pk_mul_f32 v[128:129], v[144:145], v[128:129]
	v_pk_mul_f32 v[126:127], v[142:143], v[126:127]
	v_pk_mul_f32 v[124:125], v[140:141], v[124:125]
	v_pk_mul_f32 v[122:123], v[138:139], v[122:123]
	v_pk_mul_f32 v[112:113], v[132:133], v[112:113]
	v_pk_mul_f32 v[110:111], v[130:131], v[110:111]
	v_pk_mul_f32 v[158:159], v[144:145], v[120:121]
	v_pk_mul_f32 v[160:161], v[142:143], v[118:119]
	v_cndmask_b32_e32 v1, v149, v129, vcc
	v_cndmask_b32_e32 v118, v149, v128, vcc
	v_cndmask_b32_e32 v119, v149, v127, vcc
	v_cndmask_b32_e32 v120, v149, v126, vcc
	v_pk_mul_f32 v[116:117], v[136:137], v[116:117]
	v_pk_mul_f32 v[114:115], v[134:135], v[114:115]
	v_cndmask_b32_e32 v121, v149, v125, vcc
	v_cndmask_b32_e32 v124, v149, v124, vcc
	v_cndmask_b32_e32 v123, v149, v123, vcc
	v_cndmask_b32_e32 v122, v149, v122, vcc
	v_cndmask_b32_e32 v129, v149, v113, vcc
	v_cndmask_b32_e32 v150, v149, v112, vcc
	v_cndmask_b32_e32 v157, v149, v111, vcc
	v_cndmask_b32_e32 v162, v149, v110, vcc
	ds_bpermute_b32 v110, v148, v120
	ds_bpermute_b32 v111, v148, v119
	ds_bpermute_b32 v112, v148, v118
	ds_bpermute_b32 v113, v148, v1
	v_cndmask_b32_e32 v125, v149, v117, vcc
	v_cndmask_b32_e32 v126, v149, v116, vcc
	v_cndmask_b32_e32 v127, v149, v115, vcc
	v_cndmask_b32_e32 v128, v149, v114, vcc
	ds_bpermute_b32 v114, v148, v122
	ds_bpermute_b32 v115, v148, v123
	ds_bpermute_b32 v116, v148, v124
	ds_bpermute_b32 v117, v148, v121
	ds_bpermute_b32 v118, v148, v128
	ds_bpermute_b32 v119, v148, v127
	ds_bpermute_b32 v120, v148, v126
	ds_bpermute_b32 v121, v148, v125
	ds_bpermute_b32 v122, v148, v162
	ds_bpermute_b32 v123, v148, v157
	ds_bpermute_b32 v124, v148, v150
	ds_bpermute_b32 v125, v148, v129
	v_pk_mul_f32 v[108:109], v[156:157], v[108:109] op_sel_hi:[0,1]
	v_pk_mul_f32 v[106:107], v[156:157], v[106:107] op_sel_hi:[0,1]
	v_cndmask_b32_e32 v159, v149, v159, vcc
	v_cndmask_b32_e32 v1, v149, v158, vcc
	s_waitcnt lgkmcnt(12)
	global_store_dwordx4 v[154:155], v[110:113], off
	s_waitcnt lgkmcnt(8)
	global_store_dwordx4 v[154:155], v[114:117], off offset:64
	s_waitcnt lgkmcnt(4)
	global_store_dwordx4 v[154:155], v[118:121], off offset:512
	s_waitcnt lgkmcnt(0)
	global_store_dwordx4 v[154:155], v[122:125], off offset:576
	v_cndmask_b32_e32 v111, v149, v161, vcc
	v_cndmask_b32_e32 v110, v149, v160, vcc
	v_pk_mul_f32 v[108:109], v[140:141], v[108:109]
	v_pk_mul_f32 v[106:107], v[138:139], v[106:107]
	ds_bpermute_b32 v110, v148, v110
	ds_bpermute_b32 v111, v148, v111
	ds_bpermute_b32 v112, v148, v1
	ds_bpermute_b32 v113, v148, v159
	v_cndmask_b32_e32 v1, v149, v109, vcc
	v_cndmask_b32_e32 v108, v149, v108, vcc
	v_cndmask_b32_e32 v107, v149, v107, vcc
	v_cndmask_b32_e32 v106, v149, v106, vcc
	ds_bpermute_b32 v106, v148, v106
	ds_bpermute_b32 v107, v148, v107
	ds_bpermute_b32 v108, v148, v108
	ds_bpermute_b32 v109, v148, v1
	v_lshlrev_b64 v[114:115], 12, v[152:153]
	v_lshl_add_u64 v[114:115], s[80:81], 0, v[114:115]
	v_pk_mul_f32 v[104:105], v[156:157], v[104:105] op_sel_hi:[0,1]
	v_pk_mul_f32 v[102:103], v[156:157], v[102:103] op_sel_hi:[0,1]
	v_lshl_add_u64 v[114:115], v[114:115], 0, v[146:147]
	v_pk_mul_f32 v[104:105], v[136:137], v[104:105]
	v_pk_mul_f32 v[102:103], v[134:135], v[102:103]
	v_pk_mul_f32 v[92:93], v[156:157], v[92:93] op_sel_hi:[0,1]
	v_pk_mul_f32 v[90:91], v[156:157], v[90:91] op_sel_hi:[0,1]
	v_cndmask_b32_e32 v1, v149, v105, vcc
	v_cndmask_b32_e32 v104, v149, v104, vcc
	v_cndmask_b32_e32 v103, v149, v103, vcc
	v_cndmask_b32_e32 v102, v149, v102, vcc
	v_pk_mul_f32 v[92:93], v[132:133], v[92:93]
	v_pk_mul_f32 v[90:91], v[130:131], v[90:91]
	s_waitcnt lgkmcnt(4)
	global_store_dwordx4 v[114:115], v[110:113], off
	s_waitcnt lgkmcnt(0)
	global_store_dwordx4 v[114:115], v[106:109], off offset:64
	ds_bpermute_b32 v102, v148, v102
	ds_bpermute_b32 v103, v148, v103
	ds_bpermute_b32 v104, v148, v104
	ds_bpermute_b32 v105, v148, v1
	v_cndmask_b32_e32 v1, v149, v93, vcc
	v_cndmask_b32_e32 v92, v149, v92, vcc
	v_cndmask_b32_e32 v91, v149, v91, vcc
	v_cndmask_b32_e32 v90, v149, v90, vcc
	ds_read2_b32 v[106:107], v151 offset0:32 offset1:48
	ds_bpermute_b32 v90, v148, v90
	ds_bpermute_b32 v91, v148, v91
	ds_bpermute_b32 v92, v148, v92
	ds_bpermute_b32 v93, v148, v1
	s_waitcnt lgkmcnt(5)
	global_store_dwordx4 v[114:115], v[102:105], off offset:512
	s_waitcnt lgkmcnt(0)
	global_store_dwordx4 v[114:115], v[90:93], off offset:576
	s_nop 1
	v_pk_mul_f32 v[90:91], v[106:107], v[96:97] op_sel_hi:[0,1]
	v_pk_mul_f32 v[92:93], v[106:107], v[94:95] op_sel_hi:[0,1]
	v_pk_mul_f32 v[90:91], v[144:145], v[90:91]
	v_pk_mul_f32 v[84:85], v[106:107], v[84:85] op_sel_hi:[0,1]
	v_pk_mul_f32 v[92:93], v[142:143], v[92:93]
	v_cndmask_b32_e32 v1, v149, v91, vcc
	v_pk_mul_f32 v[82:83], v[106:107], v[82:83] op_sel_hi:[0,1]
	v_pk_mul_f32 v[84:85], v[140:141], v[84:85]
	v_pk_mul_f32 v[72:73], v[106:107], v[72:73] op_sel_hi:[0,1]
	v_cndmask_b32_e32 v94, v149, v90, vcc
	v_cndmask_b32_e32 v91, v149, v93, vcc
	v_cndmask_b32_e32 v90, v149, v92, vcc
	ds_bpermute_b32 v93, v148, v1
	v_pk_mul_f32 v[82:83], v[138:139], v[82:83]
	v_cndmask_b32_e32 v1, v149, v85, vcc
	v_pk_mul_f32 v[70:71], v[106:107], v[70:71] op_sel_hi:[0,1]
	v_pk_mul_f32 v[72:73], v[136:137], v[72:73]
	v_or_b32_e32 v102, 32, v0
	ds_bpermute_b32 v90, v148, v90
	ds_bpermute_b32 v91, v148, v91
	ds_bpermute_b32 v92, v148, v94
	v_cndmask_b32_e32 v84, v149, v84, vcc
	v_cndmask_b32_e32 v83, v149, v83, vcc
	v_cndmask_b32_e32 v82, v149, v82, vcc
	ds_bpermute_b32 v85, v148, v1
	v_pk_mul_f32 v[70:71], v[134:135], v[70:71]
	v_cndmask_b32_e32 v1, v149, v73, vcc
	v_pk_mul_f32 v[60:61], v[106:107], v[60:61] op_sel_hi:[0,1]
	v_pk_mul_f32 v[58:59], v[106:107], v[58:59] op_sel_hi:[0,1]
	v_ashrrev_i32_e32 v103, 31, v102
	ds_bpermute_b32 v82, v148, v82
	ds_bpermute_b32 v83, v148, v83
	ds_bpermute_b32 v84, v148, v84
	v_cndmask_b32_e32 v72, v149, v72, vcc
	v_cndmask_b32_e32 v71, v149, v71, vcc
	v_cndmask_b32_e32 v70, v149, v70, vcc
	ds_bpermute_b32 v73, v148, v1
	v_pk_mul_f32 v[60:61], v[132:133], v[60:61]
	v_pk_mul_f32 v[58:59], v[130:131], v[58:59]
	v_lshlrev_b64 v[94:95], 12, v[102:103]
	ds_bpermute_b32 v70, v148, v70
	ds_bpermute_b32 v71, v148, v71
	ds_bpermute_b32 v72, v148, v72
	v_cndmask_b32_e32 v1, v149, v61, vcc
	v_cndmask_b32_e32 v60, v149, v60, vcc
	v_cndmask_b32_e32 v59, v149, v59, vcc
	v_cndmask_b32_e32 v58, v149, v58, vcc
	v_lshl_add_u64 v[94:95], s[80:81], 0, v[94:95]
	ds_bpermute_b32 v58, v148, v58
	ds_bpermute_b32 v59, v148, v59
	ds_bpermute_b32 v60, v148, v60
	ds_bpermute_b32 v61, v148, v1
	v_lshl_add_u64 v[94:95], v[94:95], 0, v[146:147]
	s_waitcnt lgkmcnt(12)
	global_store_dwordx4 v[94:95], v[90:93], off
	s_waitcnt lgkmcnt(8)
	global_store_dwordx4 v[94:95], v[82:85], off offset:64
	s_waitcnt lgkmcnt(4)
	global_store_dwordx4 v[94:95], v[70:73], off offset:512
	s_waitcnt lgkmcnt(0)
	global_store_dwordx4 v[94:95], v[58:61], off offset:576
	v_mov_b32_e32 v72, v107
	s_nop 0
	v_pk_mul_f32 v[58:59], v[72:73], v[64:65] op_sel_hi:[0,1]
	v_or_b32_e32 v70, 48, v0
	v_pk_mul_f32 v[60:61], v[72:73], v[62:63] op_sel_hi:[0,1]
	v_pk_mul_f32 v[58:59], v[144:145], v[58:59]
	v_ashrrev_i32_e32 v71, 31, v70
	v_pk_mul_f32 v[60:61], v[142:143], v[60:61]
	v_cndmask_b32_e32 v62, v149, v58, vcc
	v_cndmask_b32_e32 v58, v149, v60, vcc
	ds_bpermute_b32 v60, v148, v62
	v_lshlrev_b64 v[62:63], 12, v[70:71]
	v_lshl_add_u64 v[62:63], s[80:81], 0, v[62:63]
	v_lshl_add_u64 v[82:83], v[62:63], 0, v[146:147]
	v_pk_mul_f32 v[62:63], v[72:73], v[68:69] op_sel_hi:[0,1]
	v_pk_mul_f32 v[64:65], v[72:73], v[66:67] op_sel_hi:[0,1]
	v_pk_mul_f32 v[62:63], v[140:141], v[62:63]
	v_cndmask_b32_e32 v1, v149, v59, vcc
	v_cndmask_b32_e32 v59, v149, v61, vcc
	v_pk_mul_f32 v[64:65], v[138:139], v[64:65]
	v_cndmask_b32_e32 v66, v149, v62, vcc
	ds_bpermute_b32 v58, v148, v58
	ds_bpermute_b32 v59, v148, v59
	ds_bpermute_b32 v61, v148, v1
	v_cndmask_b32_e32 v1, v149, v63, vcc
	v_cndmask_b32_e32 v63, v149, v65, vcc
	v_cndmask_b32_e32 v62, v149, v64, vcc
	ds_bpermute_b32 v64, v148, v66
	v_pk_mul_f32 v[66:67], v[72:73], v[100:101] op_sel_hi:[0,1]
	ds_bpermute_b32 v62, v148, v62
	ds_bpermute_b32 v63, v148, v63
	ds_bpermute_b32 v65, v148, v1
	v_pk_mul_f32 v[68:69], v[72:73], v[98:99] op_sel_hi:[0,1]
	v_pk_mul_f32 v[66:67], v[136:137], v[66:67]
	v_pk_mul_f32 v[68:69], v[134:135], v[68:69]
	v_cndmask_b32_e32 v70, v149, v66, vcc
	v_cndmask_b32_e32 v66, v149, v68, vcc
	ds_bpermute_b32 v68, v148, v70
	v_pk_mul_f32 v[70:71], v[72:73], v[88:89] op_sel_hi:[0,1]
	v_pk_mul_f32 v[72:73], v[72:73], v[86:87] op_sel_hi:[0,1]
	v_pk_mul_f32 v[70:71], v[132:133], v[70:71]
	v_pk_mul_f32 v[72:73], v[130:131], v[72:73]
	v_cndmask_b32_e32 v84, v149, v70, vcc
	s_waitcnt lgkmcnt(5)
	global_store_dwordx4 v[82:83], v[58:61], off
	s_waitcnt lgkmcnt(1)
	global_store_dwordx4 v[82:83], v[62:65], off offset:64
	v_cndmask_b32_e32 v70, v149, v72, vcc
	ds_bpermute_b32 v72, v148, v84
	ds_read2_b32 v[84:85], v151 offset0:128 offset1:144
	v_cndmask_b32_e32 v1, v149, v67, vcc
	v_cndmask_b32_e32 v67, v149, v69, vcc
	ds_bpermute_b32 v66, v148, v66
	ds_bpermute_b32 v67, v148, v67
	ds_bpermute_b32 v69, v148, v1
	v_cndmask_b32_e32 v1, v149, v71, vcc
	v_cndmask_b32_e32 v71, v149, v73, vcc
	ds_bpermute_b32 v70, v148, v70
	ds_bpermute_b32 v71, v148, v71
	ds_bpermute_b32 v73, v148, v1
	v_add_u32_e32 v62, 0x80, v0
	v_ashrrev_i32_e32 v63, 31, v62
	s_waitcnt lgkmcnt(6)
	v_pk_mul_f32 v[58:59], v[84:85], v[80:81] op_sel_hi:[0,1]
	v_pk_mul_f32 v[60:61], v[84:85], v[78:79] op_sel_hi:[0,1]
	v_pk_mul_f32 v[58:59], v[144:145], v[58:59]
	v_lshlrev_b64 v[62:63], 12, v[62:63]
	s_waitcnt lgkmcnt(3)
	global_store_dwordx4 v[82:83], v[66:69], off offset:512
	s_waitcnt lgkmcnt(0)
	global_store_dwordx4 v[82:83], v[70:73], off offset:576
	v_pk_mul_f32 v[60:61], v[142:143], v[60:61]
	v_cndmask_b32_e32 v64, v149, v58, vcc
	v_lshl_add_u64 v[66:67], s[80:81], 0, v[62:63]
	v_pk_mul_f32 v[62:63], v[84:85], v[76:77] op_sel_hi:[0,1]
	v_cndmask_b32_e32 v1, v149, v59, vcc
	v_cndmask_b32_e32 v58, v149, v60, vcc
	ds_bpermute_b32 v60, v148, v64
	v_pk_mul_f32 v[64:65], v[84:85], v[74:75] op_sel_hi:[0,1]
	v_pk_mul_f32 v[62:63], v[140:141], v[62:63]
	v_pk_mul_f32 v[56:57], v[84:85], v[56:57] op_sel_hi:[0,1]
	v_cndmask_b32_e32 v59, v149, v61, vcc
	ds_bpermute_b32 v61, v148, v1
	v_pk_mul_f32 v[64:65], v[138:139], v[64:65]
	v_cndmask_b32_e32 v1, v149, v63, vcc
	v_pk_mul_f32 v[54:55], v[84:85], v[54:55] op_sel_hi:[0,1]
	v_pk_mul_f32 v[56:57], v[136:137], v[56:57]
	ds_bpermute_b32 v58, v148, v58
	ds_bpermute_b32 v59, v148, v59
	v_cndmask_b32_e32 v68, v149, v62, vcc
	v_cndmask_b32_e32 v63, v149, v65, vcc
	v_cndmask_b32_e32 v62, v149, v64, vcc
	ds_bpermute_b32 v65, v148, v1
	v_pk_mul_f32 v[54:55], v[134:135], v[54:55]
	v_cndmask_b32_e32 v1, v149, v57, vcc
	v_pk_mul_f32 v[48:49], v[84:85], v[48:49] op_sel_hi:[0,1]
	v_pk_mul_f32 v[46:47], v[84:85], v[46:47] op_sel_hi:[0,1]
	ds_bpermute_b32 v62, v148, v62
	ds_bpermute_b32 v63, v148, v63
	ds_bpermute_b32 v64, v148, v68
	v_cndmask_b32_e32 v56, v149, v56, vcc
	v_cndmask_b32_e32 v55, v149, v55, vcc
	v_cndmask_b32_e32 v54, v149, v54, vcc
	ds_bpermute_b32 v57, v148, v1
	v_pk_mul_f32 v[48:49], v[132:133], v[48:49]
	v_pk_mul_f32 v[46:47], v[130:131], v[46:47]
	ds_bpermute_b32 v54, v148, v54
	ds_bpermute_b32 v55, v148, v55
	ds_bpermute_b32 v56, v148, v56
	v_cndmask_b32_e32 v1, v149, v49, vcc
	v_cndmask_b32_e32 v48, v149, v48, vcc
	v_cndmask_b32_e32 v47, v149, v47, vcc
	v_cndmask_b32_e32 v46, v149, v46, vcc
	ds_bpermute_b32 v46, v148, v46
	ds_bpermute_b32 v47, v148, v47
	ds_bpermute_b32 v48, v148, v48
	ds_bpermute_b32 v49, v148, v1
	v_lshl_add_u64 v[66:67], v[66:67], 0, v[146:147]
	s_waitcnt lgkmcnt(12)
	global_store_dwordx4 v[66:67], v[58:61], off
	s_waitcnt lgkmcnt(8)
	global_store_dwordx4 v[66:67], v[62:65], off offset:64
	s_waitcnt lgkmcnt(4)
	global_store_dwordx4 v[66:67], v[54:57], off offset:512
	s_waitcnt lgkmcnt(0)
	global_store_dwordx4 v[66:67], v[46:49], off offset:576
	v_mov_b32_e32 v56, v85
	s_nop 0
	v_pk_mul_f32 v[46:47], v[56:57], v[52:53] op_sel_hi:[0,1]
	v_pk_mul_f32 v[48:49], v[56:57], v[50:51] op_sel_hi:[0,1]
	v_pk_mul_f32 v[46:47], v[144:145], v[46:47]
	v_pk_mul_f32 v[48:49], v[142:143], v[48:49]
	v_pk_mul_f32 v[44:45], v[56:57], v[44:45] op_sel_hi:[0,1]
	v_pk_mul_f32 v[42:43], v[56:57], v[42:43] op_sel_hi:[0,1]
	v_cndmask_b32_e32 v1, v149, v47, vcc
	v_cndmask_b32_e32 v50, v149, v46, vcc
	v_cndmask_b32_e32 v47, v149, v49, vcc
	v_cndmask_b32_e32 v46, v149, v48, vcc
	v_pk_mul_f32 v[44:45], v[140:141], v[44:45]
	v_pk_mul_f32 v[42:43], v[138:139], v[42:43]
	v_add_u32_e32 v54, 0x90, v0
	ds_bpermute_b32 v46, v148, v46
	ds_bpermute_b32 v47, v148, v47
	ds_bpermute_b32 v48, v148, v50
	ds_bpermute_b32 v49, v148, v1
	v_cndmask_b32_e32 v1, v149, v45, vcc
	v_cndmask_b32_e32 v44, v149, v44, vcc
	v_cndmask_b32_e32 v43, v149, v43, vcc
	v_cndmask_b32_e32 v42, v149, v42, vcc
	v_ashrrev_i32_e32 v55, 31, v54
	ds_bpermute_b32 v42, v148, v42
	ds_bpermute_b32 v43, v148, v43
	ds_bpermute_b32 v44, v148, v44
	ds_bpermute_b32 v45, v148, v1
	v_lshlrev_b64 v[50:51], 12, v[54:55]
	v_lshl_add_u64 v[50:51], s[80:81], 0, v[50:51]
	v_pk_mul_f32 v[40:41], v[56:57], v[40:41] op_sel_hi:[0,1]
	v_pk_mul_f32 v[38:39], v[56:57], v[38:39] op_sel_hi:[0,1]
	v_lshl_add_u64 v[50:51], v[50:51], 0, v[146:147]
	v_pk_mul_f32 v[40:41], v[136:137], v[40:41]
	v_pk_mul_f32 v[38:39], v[134:135], v[38:39]
	v_pk_mul_f32 v[32:33], v[56:57], v[32:33] op_sel_hi:[0,1]
	v_pk_mul_f32 v[30:31], v[56:57], v[30:31] op_sel_hi:[0,1]
	v_cndmask_b32_e32 v1, v149, v41, vcc
	v_cndmask_b32_e32 v40, v149, v40, vcc
	v_cndmask_b32_e32 v39, v149, v39, vcc
	v_cndmask_b32_e32 v38, v149, v38, vcc
	v_pk_mul_f32 v[32:33], v[132:133], v[32:33]
	v_pk_mul_f32 v[30:31], v[130:131], v[30:31]
	s_waitcnt lgkmcnt(4)
	global_store_dwordx4 v[50:51], v[46:49], off
	s_waitcnt lgkmcnt(0)
	global_store_dwordx4 v[50:51], v[42:45], off offset:64
	ds_bpermute_b32 v38, v148, v38
	ds_bpermute_b32 v39, v148, v39
	ds_bpermute_b32 v40, v148, v40
	ds_bpermute_b32 v41, v148, v1
	v_cndmask_b32_e32 v1, v149, v33, vcc
	v_cndmask_b32_e32 v32, v149, v32, vcc
	v_cndmask_b32_e32 v31, v149, v31, vcc
	v_cndmask_b32_e32 v30, v149, v30, vcc
	ds_read2_b32 v[42:43], v151 offset0:160 offset1:176
	ds_bpermute_b32 v30, v148, v30
	ds_bpermute_b32 v31, v148, v31
	ds_bpermute_b32 v32, v148, v32
	ds_bpermute_b32 v33, v148, v1
	s_waitcnt lgkmcnt(5)
	global_store_dwordx4 v[50:51], v[38:41], off offset:512
	s_waitcnt lgkmcnt(0)
	global_store_dwordx4 v[50:51], v[30:33], off offset:576
	s_nop 1
	v_pk_mul_f32 v[30:31], v[42:43], v[36:37] op_sel_hi:[0,1]
	v_pk_mul_f32 v[32:33], v[42:43], v[34:35] op_sel_hi:[0,1]
	v_pk_mul_f32 v[30:31], v[144:145], v[30:31]
	v_pk_mul_f32 v[32:33], v[142:143], v[32:33]
	v_pk_mul_f32 v[28:29], v[42:43], v[28:29] op_sel_hi:[0,1]
	v_pk_mul_f32 v[26:27], v[42:43], v[26:27] op_sel_hi:[0,1]
	v_pk_mul_f32 v[22:23], v[42:43], v[22:23] op_sel_hi:[0,1]
	v_cndmask_b32_e32 v1, v149, v31, vcc
	v_cndmask_b32_e32 v34, v149, v30, vcc
	v_cndmask_b32_e32 v31, v149, v33, vcc
	v_cndmask_b32_e32 v30, v149, v32, vcc
	v_pk_mul_f32 v[28:29], v[140:141], v[28:29]
	v_pk_mul_f32 v[26:27], v[138:139], v[26:27]
	v_pk_mul_f32 v[24:25], v[42:43], v[24:25] op_sel_hi:[0,1]
	v_pk_mul_f32 v[22:23], v[134:135], v[22:23]
	v_add_u32_e32 v38, 0xa0, v0
	ds_bpermute_b32 v30, v148, v30
	ds_bpermute_b32 v31, v148, v31
	ds_bpermute_b32 v32, v148, v34
	ds_bpermute_b32 v33, v148, v1
	v_cndmask_b32_e32 v1, v149, v29, vcc
	v_cndmask_b32_e32 v28, v149, v28, vcc
	v_cndmask_b32_e32 v27, v149, v27, vcc
	v_cndmask_b32_e32 v26, v149, v26, vcc
	v_pk_mul_f32 v[24:25], v[136:137], v[24:25]
	v_cndmask_b32_e32 v23, v149, v23, vcc
	v_pk_mul_f32 v[16:17], v[42:43], v[16:17] op_sel_hi:[0,1]
	v_pk_mul_f32 v[14:15], v[42:43], v[14:15] op_sel_hi:[0,1]
	v_ashrrev_i32_e32 v39, 31, v38
	ds_bpermute_b32 v26, v148, v26
	ds_bpermute_b32 v27, v148, v27
	ds_bpermute_b32 v28, v148, v28
	ds_bpermute_b32 v29, v148, v1
	v_cndmask_b32_e32 v1, v149, v25, vcc
	v_cndmask_b32_e32 v24, v149, v24, vcc
	v_cndmask_b32_e32 v22, v149, v22, vcc
	ds_bpermute_b32 v23, v148, v23
	v_pk_mul_f32 v[16:17], v[132:133], v[16:17]
	v_pk_mul_f32 v[14:15], v[130:131], v[14:15]
	v_lshlrev_b64 v[34:35], 12, v[38:39]
	ds_bpermute_b32 v22, v148, v22
	ds_bpermute_b32 v24, v148, v24
	ds_bpermute_b32 v25, v148, v1
	v_cndmask_b32_e32 v1, v149, v17, vcc
	v_cndmask_b32_e32 v16, v149, v16, vcc
	v_cndmask_b32_e32 v15, v149, v15, vcc
	v_cndmask_b32_e32 v14, v149, v14, vcc
	v_lshl_add_u64 v[34:35], s[80:81], 0, v[34:35]
	ds_bpermute_b32 v14, v148, v14
	ds_bpermute_b32 v15, v148, v15
	ds_bpermute_b32 v16, v148, v16
	ds_bpermute_b32 v17, v148, v1
	v_lshl_add_u64 v[34:35], v[34:35], 0, v[146:147]
	s_waitcnt lgkmcnt(12)
	global_store_dwordx4 v[34:35], v[30:33], off
	s_waitcnt lgkmcnt(8)
	global_store_dwordx4 v[34:35], v[26:29], off offset:64
	s_waitcnt lgkmcnt(4)
	global_store_dwordx4 v[34:35], v[22:25], off offset:512
	s_waitcnt lgkmcnt(0)
	global_store_dwordx4 v[34:35], v[14:17], off offset:576
	v_add_u32_e32 v0, 0xb0, v0
	v_mov_b32_e32 v22, v43
	v_pk_mul_f32 v[14:15], v[22:23], v[20:21] op_sel_hi:[0,1]
	v_ashrrev_i32_e32 v1, 31, v0
	v_pk_mul_f32 v[16:17], v[22:23], v[18:19] op_sel_hi:[0,1]
	v_pk_mul_f32 v[14:15], v[144:145], v[14:15]
	v_pk_mul_f32 v[16:17], v[142:143], v[16:17]
	v_cndmask_b32_e32 v18, v149, v15, vcc
	v_cndmask_b32_e32 v19, v149, v14, vcc
	v_lshlrev_b64 v[0:1], 12, v[0:1]
	v_cndmask_b32_e32 v15, v149, v17, vcc
	v_cndmask_b32_e32 v14, v149, v16, vcc
	ds_bpermute_b32 v16, v148, v19
	ds_bpermute_b32 v17, v148, v18
	v_lshl_add_u64 v[18:19], s[80:81], 0, v[0:1]
	v_pk_mul_f32 v[0:1], v[22:23], v[12:13] op_sel_hi:[0,1]
	v_pk_mul_f32 v[0:1], v[140:141], v[0:1]
	v_pk_mul_f32 v[10:11], v[22:23], v[10:11] op_sel_hi:[0,1]
	v_cndmask_b32_e32 v1, v149, v1, vcc
	v_cndmask_b32_e32 v0, v149, v0, vcc
	ds_bpermute_b32 v12, v148, v0
	ds_bpermute_b32 v13, v148, v1
	v_pk_mul_f32 v[0:1], v[22:23], v[8:9] op_sel_hi:[0,1]
	v_pk_mul_f32 v[0:1], v[136:137], v[0:1]
	v_pk_mul_f32 v[10:11], v[138:139], v[10:11]
	v_pk_mul_f32 v[6:7], v[22:23], v[6:7] op_sel_hi:[0,1]
	v_cndmask_b32_e32 v1, v149, v1, vcc
	v_cndmask_b32_e32 v0, v149, v0, vcc
	ds_bpermute_b32 v14, v148, v14
	ds_bpermute_b32 v15, v148, v15
	v_cndmask_b32_e32 v11, v149, v11, vcc
	v_cndmask_b32_e32 v10, v149, v10, vcc
	v_pk_mul_f32 v[6:7], v[134:135], v[6:7]
	ds_bpermute_b32 v8, v148, v0
	ds_bpermute_b32 v9, v148, v1
	v_pk_mul_f32 v[0:1], v[22:23], v[4:5] op_sel_hi:[0,1]
	v_pk_mul_f32 v[2:3], v[22:23], v[2:3] op_sel_hi:[0,1]
	ds_bpermute_b32 v10, v148, v10
	ds_bpermute_b32 v11, v148, v11
	v_cndmask_b32_e32 v7, v149, v7, vcc
	v_cndmask_b32_e32 v6, v149, v6, vcc
	v_pk_mul_f32 v[0:1], v[132:133], v[0:1]
	v_pk_mul_f32 v[2:3], v[130:131], v[2:3]
	ds_bpermute_b32 v6, v148, v6
	ds_bpermute_b32 v7, v148, v7
	v_cndmask_b32_e32 v4, v149, v1, vcc
	v_cndmask_b32_e32 v5, v149, v0, vcc
	v_cndmask_b32_e32 v1, v149, v3, vcc
	v_cndmask_b32_e32 v0, v149, v2, vcc
	ds_bpermute_b32 v0, v148, v0
	ds_bpermute_b32 v1, v148, v1
	ds_bpermute_b32 v2, v148, v5
	ds_bpermute_b32 v3, v148, v4
	v_lshl_add_u64 v[4:5], v[18:19], 0, v[146:147]
	s_waitcnt lgkmcnt(10)
	global_store_dwordx4 v[4:5], v[14:17], off
	s_waitcnt lgkmcnt(6)
	global_store_dwordx4 v[4:5], v[10:13], off offset:64
	s_waitcnt lgkmcnt(4)
	global_store_dwordx4 v[4:5], v[6:9], off offset:512
	s_waitcnt lgkmcnt(0)
	global_store_dwordx4 v[4:5], v[0:3], off offset:576
